# even scans (GLA/HGRN2): ostore pseudo-loops replaced by straight-line stores with hoisted per-thread address constants; zero-padded state-update MFMAs issued as 16x16x16 bf16
# baseline (speedup 1.0000x reference)
; template <int MODE>
; __device__ void scan_unit(int swave, const Params& p, int j, int b, int h, int dir, char* shm) {
;     ...
;   f32x4 S[4][NVT];
; #pragma unroll
;   for (int a = 0; a < 4; ++a)
; #pragma unroll
;     for (int t = 0; t < NVT; ++t) S[a][t] = (f32x4){0.f, 0.f, 0.f, 0.f};
;   auto compute = [&](const char* buf, bf16_t* obuf) {
;     const bf16_t* qin = (const bf16_t*)buf; const bf16_t* ktil = (const bf16_t*)(buf + OFF_KT); const bf16_t* koutT = (const bf16_t*)(buf + OFF_KO);
;     const bf16_t* vT = (const bf16_t*)(buf + OFF_VT); const float* dec = (const float*)(buf + OFF_DEC);
;     bf16x8 Asc = {0, 0, 0, 0, 0, 0, 0, 0};
;     if (KS == 1 || wk == 0) {
;       f32x4 sc = {0.f, 0.f, 0.f, 0.f};
; #pragma unroll
;       for (int m = 0; m < DK / 32; ++m) {
;         const bf16x8 a = *(const bf16x8*)(ktil + r * QS + m * 32 + q4 * 8);
;         const bf16x8 bb = *(const bf16x8*)(qin + r * QS + m * 32 + q4 * 8);
;         sc = __builtin_amdgcn_mfma_f32_16x16x32_bf16(a, bb, sc, 0, 0, 0);
;       }
;       {
;         const unsigned p01 = pk2(q4 * 4 + 0 > r ? 0.f : sc[0], q4 * 4 + 1 > r ? 0.f : sc[1]);
;         const unsigned p23 = pk2(q4 * 4 + 2 > r ? 0.f : sc[2], q4 * 4 + 3 > r ? 0.f : sc[3]);
;     ...
;   constexpr int NIT = NCH / 2, OB1 = KS * 16 * OS;
;   auto bufp = [&](int stage, int sub) { return buf0 + (stage * 2 + sub) * BUFB; };
;   auto obp = [&](int stage, int sub) { return obuf0 + (stage * 2 + sub) * OB1; };
;   Raw a0, a1, b0, b1;
;   __syncthreads();
;   load_raw(0, a0); load_raw(1, a1);
;   stage2(a0, bufp(0, 0), 0); stage2(a1, bufp(0, 1), 1);
;   load_raw(2, a0); load_raw(3, a1);
;   lds_barrier();
;   auto body = [&](int it, Raw& c0, Raw& c1, Raw& n0, Raw& n1) {
;     touch(c0); touch(c1);
;     __builtin_amdgcn_sched_barrier(0);
;     const int cA = 2 * it + 4 < NCH ? 2 * it + 4 : NCH - 2;
;     load_raw(cA, n0); load_raw(cA + 1, n1);
;     if (it > 0) { ostore(2 * it - 2, obp((it - 1) & 1, 0)); ostore(2 * it - 1, obp((it - 1) & 1, 1)); }
;     stage2(c0, bufp((it + 1) & 1, 0), 0); stage2(c1, bufp((it + 1) & 1, 1), 0);
;     compute(bufp(it & 1, 0), obp(it & 1, 0)); compute(bufp(it & 1, 1), obp(it & 1, 1));
;     lds_barrier();
;   };
;   for (int it = 0; it < NIT; it += 2) { body(it, a0, a1, b0, b1); body(it + 1, b0, b1, a0, a1); }
.LBB0_645:
	s_or_b64 exec, exec, s[4:5]
	v_readlane_b32 s4, v248, 8
	v_readlane_b32 s6, v248, 10
	v_readlane_b32 s5, v248, 9
	v_readlane_b32 s7, v248, 11
	s_add_u32 s4, s6, s2
	s_addc_u32 s5, s7, s3
	v_or_b32_e32 v0, 32, v37
	v_xor_b32_e32 v2, 0x7df, v37
	s_and_b64 s[2:3], s[0:1], exec
	v_cndmask_b32_e64 v0, v2, v0, s[0:1]
	s_cselect_b32 s2, 0, 0x4000000
	v_or_b32_e32 v0, s46, v0
	v_mov_b64_e32 v[6:7], s[48:49]
	s_add_u32 s4, s4, s2
	v_mad_u64_u32 v[10:11], s[2:3], v0, s53, v[6:7]
	v_or_b32_e32 v0, 48, v37
	v_xor_b32_e32 v2, 0x7cf, v37
	v_cndmask_b32_e64 v0, v2, v0, s[0:1]
	s_addc_u32 s5, s5, 0
	s_lshl_b32 s70, s8, 1
	v_or_b32_e32 v0, s46, v0
	s_mov_b32 s72, s70
	s_mov_b32 s73, s95
	v_mad_i32_i24 v11, s47, v156, v11
	v_mad_u64_u32 v[6:7], s[2:3], v0, s53, v[6:7]
	v_lshl_add_u64 v[12:13], v[10:11], 0, s[50:51]
	v_lshl_add_u64 v[14:15], v[10:11], 0, s[94:95]
	v_lshl_add_u64 v[10:11], v[10:11], 0, s[72:73]
	v_mad_i32_i24 v7, s47, v156, v7
	v_lshl_add_u64 v[10:11], v[10:11], 0, v[26:27]
	v_lshl_add_u64 v[18:19], v[6:7], 0, s[94:95]
	v_lshl_add_u64 v[12:13], v[12:13], 0, v[22:23]
	v_lshl_add_u64 v[14:15], v[14:15], 0, s[50:51]
	v_add_co_u32_e32 v10, vcc, s62, v10
	v_lshl_add_u64 v[16:17], v[6:7], 0, s[50:51]
	v_lshl_add_u64 v[18:19], v[18:19], 0, s[50:51]
	v_lshl_add_u64 v[6:7], v[6:7], 0, s[72:73]
	v_lshl_add_u64 v[14:15], v[14:15], 0, v[22:23]
	v_addc_co_u32_e32 v11, vcc, 0, v11, vcc
	v_lshl_add_u64 v[16:17], v[16:17], 0, v[22:23]
	v_lshl_add_u64 v[18:19], v[18:19], 0, v[22:23]
	global_load_dword v57, v[12:13], off offset:3136
	global_load_dword v59, v[14:15], off
	global_load_dwordx2 v[30:31], v[10:11], off offset:576
	global_load_dword v54, v[16:17], off offset:3136
	global_load_dword v55, v[18:19], off
	v_lshl_add_u64 v[6:7], v[6:7], 0, v[26:27]
	v_add_co_u32_e32 v6, vcc, s62, v6
	v_lshrrev_b32_e32 v0, 4, v1
	s_nop 0
	v_addc_co_u32_e32 v7, vcc, 0, v7, vcc
	global_load_dwordx2 v[28:29], v[6:7], off offset:576
	s_add_u32 s2, s4, s70
	s_waitcnt vmcnt(6)
	ds_write_b16 v42, v4 offset:18688
	ds_write_b16_d16_hi v42, v4 offset:18728
	ds_write_b16 v42, v5 offset:18768
	ds_write_b16_d16_hi v42, v5 offset:18808
	v_lshlrev_b32_e32 v4, 2, v0
	s_addc_u32 s3, s5, 0
	v_cmp_gt_u32_e64 s[6:7], v4, v37
	v_cmp_lt_u32_e64 s[8:9], v4, v37
	v_or_b32_e32 v5, 2, v4
	v_or_b32_e32 v4, 3, v4
	s_add_u32 s68, s2, 0x4000400
	s_movk_i32 s2, 0x200
	v_cmp_gt_u32_e64 s[12:13], v4, v37
	v_ashrrev_i32_e32 v4, 2, v36
	v_cmp_gt_i32_e64 s[4:5], s2, v36
	v_and_or_b32 v4, v4, -16, v37
	s_movk_i32 s2, 0x210
	v_lshlrev_b32_e32 v2, 3, v0
	v_mad_u32_u24 v0, v0, s2, v4
	v_lshl_add_u32 v48, v0, 1, 0
	v_lshlrev_b32_e32 v0, 5, v37
	v_add3_u32 v49, 0, v0, v2
	v_lshlrev_b32_e32 v0, 3, v36
	v_readlane_b32 s2, v247, 39
	s_waitcnt lgkmcnt(0)
	s_barrier
	v_and_b32_e32 v1, 48, v1
	v_add_u32_e32 v45, s2, v0
	v_readlane_b32 s2, v247, 40
	v_cmp_gt_u32_e64 s[10:11], v5, v37
	v_mul_lo_u32 v5, v4, 40
	v_add_u32_e32 v44, s2, v0
	v_readlane_b32 s2, v247, 41
	v_add_u32_e32 v46, v8, v1
	v_add3_u32 v47, 0, v5, v2
	v_sub_u32_e32 v5, 0, v2
	v_add_u32_e32 v51, s2, v0
	v_readlane_b32 s2, v247, 42
	v_mov_b32_e32 v4, 0
	s_mov_b32 s35, 0
	s_addc_u32 s69, s3, 0
	v_add_u32_e32 v50, 0, v1
	v_lshlrev_b32_e32 v43, 2, v36
	v_add_u32_e32 v52, s2, v0
	v_add_u32_e32 v53, v46, v5
	v_mov_b32_e32 v5, v4
	v_mov_b32_e32 v6, v4
	v_mov_b32_e32 v7, v4
	v_mov_b32_e32 v8, v4
	v_mov_b32_e32 v9, v4
	v_mov_b32_e32 v10, v4
	v_mov_b32_e32 v11, v4
	v_mov_b32_e32 v12, v4
	v_mov_b32_e32 v13, v4
	v_mov_b32_e32 v14, v4
	v_mov_b32_e32 v15, v4
	v_mov_b32_e32 v16, v4
	v_mov_b32_e32 v17, v4
	v_mov_b32_e32 v18, v4
	v_mov_b32_e32 v19, v4
	v_lshrrev_b32_e32 v166, 5, v147
	v_sub_u32_e32 v167, 15, v166
	v_cndmask_b32_e64 v167, v167, v166, s[0:1]
	v_lshlrev_b32_e32 v167, 11, v167
	v_and_b32_e32 v168, 31, v147
	v_lshl_add_u32 v167, v168, 3, v167
	v_add_u32_e32 v168, 0x8000, v167
	v_cndmask_b32_e64 v169, v168, v167, s[0:1]
	v_cndmask_b32_e64 v168, v167, v168, s[0:1]
	v_mov_b32_e32 v167, v169
	v_lshlrev_b32_e32 v166, 3, v166
	s_branch .LBB0_647
.LBB0_646:
	s_or_b64 exec, exec, s[2:3]
	ds_write_b16 v42, v32 offset:18688
	ds_write_b16_d16_hi v42, v32 offset:18728
	ds_write_b16 v42, v33 offset:18768
	ds_write_b16_d16_hi v42, v33 offset:18808
	ds_read_b128 v[32:35], v46 offset:26368
	ds_read_b128 v[64:67], v46 offset:24064
	ds_read_b128 v[68:71], v46 offset:26432
	ds_read_b128 v[72:75], v46 offset:24128
	v_add_u32_e32 v0, 0x5800, v53
	v_add_u32_e32 v56, 0x8800, v53
	s_waitcnt lgkmcnt(2)
	v_mfma_f32_16x16x32_bf16 v[32:35], v[32:35], v[64:67], 0
	ds_read_b64 v[64:65], v47 offset:30720
	ds_read2_b64 v[76:79], v0 offset0:192 offset1:196
	ds_read2_b64 v[80:83], v0 offset0:200 offset1:204
	v_mov_b32_e32 v66, v3
	v_mov_b32_e32 v67, v3
	s_waitcnt lgkmcnt(3)
	v_mfma_f32_16x16x32_bf16 v[32:35], v[68:71], v[72:75], v[32:35]
	s_waitcnt lgkmcnt(1)
	v_bfi_b32 v78, s30, v78, v78
	s_waitcnt lgkmcnt(0)
	v_bfi_b32 v82, s30, v82, v82
	v_cvt_pk_bf16_f32 v68, v8, v9
	v_cvt_pk_bf16_f32 v69, v10, v11
	v_cvt_pk_bf16_f32 v70, v12, v13
	s_nop 0
	v_cndmask_b32_e64 v0, v32, 0, s[6:7]
	v_cndmask_b32_e64 v1, 0, v33, s[8:9]
	v_cndmask_b32_e64 v2, v34, 0, s[10:11]
	v_cndmask_b32_e64 v32, v35, 0, s[12:13]
	v_cvt_pk_bf16_f32 v0, v0, v1
	v_cvt_pk_bf16_f32 v1, v2, v32
	v_mov_b32_e32 v2, v3
	v_cvt_pk_bf16_f32 v71, v14, v15
	s_add_i32 s35, s35, 2
	v_mfma_f32_16x16x32_bf16 v[32:35], v[0:3], v[64:67], 0
	s_and_b64 vcc, exec, s[74:75]
	v_mfma_f32_16x16x32_bf16 v[32:35], v[76:79], v[68:71], v[32:35]
	v_cvt_pk_bf16_f32 v68, v16, v17
	v_cvt_pk_bf16_f32 v69, v18, v19
	v_cvt_pk_bf16_f32 v70, v4, v5
	v_cvt_pk_bf16_f32 v71, v6, v7
	s_nop 1
	v_mfma_f32_16x16x32_bf16 v[32:35], v[80:83], v[68:71], v[32:35]
	s_nop 7
	v_cvt_pk_bf16_f32 v0, v32, s0
	ds_write_b16 v48, v0 offset:56576
	v_cvt_pk_bf16_f32 v0, v33, s0
	ds_write_b16 v48, v0 offset:56840
	v_cvt_pk_bf16_f32 v0, v34, s0
	ds_write_b16 v48, v0 offset:57104
	v_cvt_pk_bf16_f32 v0, v35, s0
	ds_write_b16 v48, v0 offset:57368
	ds_read2st64_b64 v[32:35], v49 offset0:56 offset1:57
	ds_read2st64_b64 v[68:71], v49 offset0:58 offset1:59
	ds_read_b128 v[72:75], v50 offset:35840
	ds_read_b128 v[76:79], v50 offset:35904
	s_waitcnt lgkmcnt(3)
; __device__ __forceinline__ float lo_bf(unsigned u) { return __uint_as_float(u << 16); }
; template <int MODE>
; __device__ void scan_unit(int swave, const Params& p, int j, int b, int h, int dir, char* shm) {
;     ...
;   auto load_raw = [&](int c, Raw& R) {
;     const int tok = tokof(c, ti);
;     const bf16_t* row = P + (rowbase + tok) * LDP;
;     if (MODE == 0) {
;       R.q = *(const unsigned*)(row + E_GQ + h * 64 + dp); R.k = *(const unsigned*)(row + E_GK + h * 64 + dp);
;       const uint4* lrp = (const uint4*)(row + (dir ? E_GLB : E_GLF));
;       R.lr0 = lrp[0]; R.lr1 = lrp[1];
;       R.v = *(const uint2*)(row + E_GV + h * 128 + vg * 4);
;     } else if (MODE == 1) {
;       R.q = *(const unsigned*)(row + E_HQ + h * 64 + dp); R.k = *(const unsigned*)(row + (dir ? E_HZB : E_HZF) + h * 64 + dp);
;       R.v = *(const uint2*)(row + E_HI + h * 128 + vg * 4);
;     } else {
;       R.q = *(const unsigned*)(row + O_RQ + h * 128 + dp); R.q2 = *(const unsigned*)(row + O_RQ + h * 128 + 64 + dp);
;       R.k = *(const unsigned*)(row + O_RK + h * 128 + dp); R.k2 = *(const unsigned*)(row + O_RK + h * 128 + 64 + dp);
;       R.cs = *(const float4*)(rope + tok * 64 + dp);
;       const unsigned* vp = (const unsigned*)(row + O_RV + h * 192 + vg * 6);
;       R.v30 = vp[0]; R.v31 = vp[1]; R.v32 = vp[2];
;     }
;   };
;     ...
;     for (int kt = 0; kt < 4; ++kt) {
;       const uint2 kk = *(const uint2*)(koutT + (slab + kt * 16 + r) * 16 + q4 * 4);
;       const bf16x8 Ak = {(short)(kk.x & 0xffff), (short)(kk.x >> 16), (short)(kk.y & 0xffff), (short)(kk.y >> 16), 0, 0, 0, 0};
;       const f32x4 dc = *(const f32x4*)(dec + slab + kt * 16 + q4 * 4);
; #pragma unroll
;       for (int t = 0; t < NVT; ++t) S[kt][t] = __builtin_amdgcn_mfma_f32_16x16x32_bf16(Ak, Bv[t], S[kt][t] * dc, 0, 0, 0);
;     }
;   };
;   auto ostore = [&](int c, const bf16_t* obuf) {
;     for (int idx = tid; idx < 16 * DV / 4; idx += 512) {
;       const int i = idx / (DV / 4), cc = (idx % (DV / 4)) * 4;
;       uint2 o = *(const uint2*)(obuf + i * OS + cc);
;       if (KS == 2) {
;         const uint2 o2 = *(const uint2*)(obuf + (16 + i) * OS + cc);
;         o.x = pk2(lo_bf(o.x) + lo_bf(o2.x), hi_bf(o.x) + hi_bf(o2.x)); o.y = pk2(lo_bf(o.y) + lo_bf(o2.y), hi_bf(o.y) + hi_bf(o2.y));
;       }
;       *(uint2*)(O + (rowbase + tokof(c, i)) * OLD + cc) = o;
;     }
	s_waitcnt lgkmcnt(1)
	v_pk_mul_f32 v[10:11], v[10:11], v[74:75]
	v_pk_mul_f32 v[8:9], v[8:9], v[72:73]
	s_waitcnt lgkmcnt(0)
	v_pk_mul_f32 v[14:15], v[14:15], v[78:79]
	v_pk_mul_f32 v[12:13], v[12:13], v[76:77]
	v_mfma_f32_16x16x16_bf16 v[8:11], v[32:33], v[64:65], v[8:11]
	v_mov_b32_e32 v0, v34
	v_mov_b32_e32 v1, v35
	ds_read_b128 v[32:35], v50 offset:35968
	ds_read_b128 v[72:75], v50 offset:36032
	v_mfma_f32_16x16x16_bf16 v[12:15], v[0:1], v[64:65], v[12:15]
	s_waitcnt lgkmcnt(1)
	v_pk_mul_f32 v[18:19], v[18:19], v[34:35]
	v_pk_mul_f32 v[16:17], v[16:17], v[32:33]
	v_cvt_pk_bf16_f32 v76, v8, v9
	v_cvt_pk_bf16_f32 v77, v10, v11
	v_mfma_f32_16x16x16_bf16 v[32:35], v[68:69], v[64:65], v[16:19]
	s_nop 1
	v_cvt_pk_bf16_f32 v78, v12, v13
	ds_read_b128 v[16:19], v46 offset:38400
	s_waitcnt lgkmcnt(1)
	v_pk_mul_f32 v[6:7], v[6:7], v[74:75]
	v_pk_mul_f32 v[4:5], v[4:5], v[72:73]
	v_cvt_pk_bf16_f32 v79, v14, v15
	s_nop 0
	v_mfma_f32_16x16x16_bf16 v[4:7], v[70:71], v[64:65], v[4:7]
	ds_read_b128 v[64:67], v46 offset:38464
	ds_read_b128 v[68:71], v46 offset:36096
	ds_read_b128 v[72:75], v46 offset:36160
	s_waitcnt lgkmcnt(1)
	v_mfma_f32_16x16x32_bf16 v[16:19], v[16:19], v[68:71], 0
	v_mov_b32_e32 v70, v3
	v_mov_b32_e32 v71, v3
	s_waitcnt lgkmcnt(0)
	v_mfma_f32_16x16x32_bf16 v[16:19], v[64:67], v[72:75], v[16:19]
	s_nop 7
	v_cndmask_b32_e64 v0, v16, 0, s[6:7]
	v_cndmask_b32_e64 v1, 0, v17, s[8:9]
	v_cvt_pk_bf16_f32 v0, v0, v1
	v_cndmask_b32_e64 v1, v18, 0, s[10:11]
	v_cndmask_b32_e64 v2, v19, 0, s[12:13]
	ds_read2_b64 v[16:19], v56 offset0:160 offset1:164
	ds_read2_b64 v[64:67], v56 offset0:168 offset1:172
	v_cvt_pk_bf16_f32 v1, v1, v2
	ds_read_b64 v[68:69], v47 offset:42752
	v_mov_b32_e32 v2, v3
	s_waitcnt lgkmcnt(2)
	v_bfi_b32 v18, s30, v18, v18
	s_waitcnt lgkmcnt(1)
	v_bfi_b32 v66, s30, v66, v66
	s_waitcnt lgkmcnt(0)
	v_mfma_f32_16x16x32_bf16 v[72:75], v[0:3], v[68:71], 0
	v_mfma_f32_16x16x32_bf16 v[16:19], v[16:19], v[76:79], v[72:75]
	s_nop 6
	v_cvt_pk_bf16_f32 v72, v32, v33
	v_cvt_pk_bf16_f32 v73, v34, v35
	v_cvt_pk_bf16_f32 v74, v4, v5
	v_cvt_pk_bf16_f32 v75, v6, v7
	s_nop 1
	v_mfma_f32_16x16x32_bf16 v[16:19], v[64:67], v[72:75], v[16:19]
	s_nop 7
	v_cvt_pk_bf16_f32 v0, v16, s0
	ds_write_b16 v48, v0 offset:60800
	v_cvt_pk_bf16_f32 v0, v17, s0
	ds_write_b16 v48, v0 offset:61064
	v_cvt_pk_bf16_f32 v0, v18, s0
	ds_write_b16 v48, v0 offset:61328
	v_cvt_pk_bf16_f32 v0, v19, s0
	ds_write_b16 v48, v0 offset:61592
	ds_read2st64_b64 v[64:67], v62 offset0:79 offset1:80
	ds_read2st64_b64 v[60:63], v62 offset0:81 offset1:82
	ds_read_b128 v[16:19], v50 offset:47872
	ds_read_b128 v[72:75], v50 offset:47936
	s_waitcnt lgkmcnt(3)
	s_waitcnt lgkmcnt(1)
	v_pk_mul_f32 v[10:11], v[10:11], v[18:19]
	v_pk_mul_f32 v[8:9], v[8:9], v[16:17]
	s_nop 1
	v_mfma_f32_16x16x16_bf16 v[16:19], v[64:65], v[68:69], v[8:11]
	v_mov_b32_e32 v0, v66
	v_mov_b32_e32 v1, v67
	ds_read_b128 v[64:67], v50 offset:48064
	s_waitcnt lgkmcnt(1)
	v_pk_mul_f32 v[10:11], v[14:15], v[74:75]
	v_pk_mul_f32 v[8:9], v[12:13], v[72:73]
	s_waitcnt lgkmcnt(0)
	v_pk_mul_f32 v[6:7], v[6:7], v[66:67]
	v_mfma_f32_16x16x16_bf16 v[12:15], v[0:1], v[68:69], v[8:11]
	v_pk_mul_f32 v[4:5], v[4:5], v[64:65]
	ds_read_b128 v[8:11], v50 offset:48000
	s_waitcnt lgkmcnt(0)
	s_barrier
	s_waitcnt lgkmcnt(0)
	v_pk_mul_f32 v[10:11], v[34:35], v[10:11]
	v_pk_mul_f32 v[8:9], v[32:33], v[8:9]
	s_nop 1
	v_mfma_f32_16x16x16_bf16 v[8:11], v[60:61], v[68:69], v[8:11]
	v_mov_b32_e32 v0, v62
	v_mov_b32_e32 v1, v63
	s_nop 1
	v_mfma_f32_16x16x16_bf16 v[4:7], v[62:63], v[68:69], v[4:7]
	s_cbranch_vccnz .LBB0_665
.LBB0_647:
	s_waitcnt vmcnt(3)
	s_waitcnt vmcnt(0)
	s_cmp_gt_u32 s35, 61
	s_cselect_b64 s[74:75], -1, 0
	s_lshl_b32 s20, s35, 5
	s_add_i32 s18, s20, 64
	s_cmp_lt_u32 s35, 62
	s_cselect_b64 s[2:3], -1, 0
	s_and_b64 s[16:17], s[2:3], exec
	s_cselect_b32 s16, s18, 0x7e0
	v_or_b32_e32 v2, s16, v37
	v_sub_u32_e32 v0, 0x7ff, v2
	v_cndmask_b32_e64 v0, v0, v2, s[0:1]
	v_ashrrev_i32_e32 v1, 31, v0
	v_lshl_add_u64 v[0:1], s[46:47], 0, v[0:1]
	v_mov_b64_e32 v[32:33], s[48:49]
	v_mad_u64_u32 v[34:35], s[16:17], v0, s53, v[32:33]
	v_mad_i32_i24 v35, v1, s53, v35
	v_lshl_add_u64 v[60:61], v[34:35], 0, s[94:95]
	v_or_b32_e32 v2, 16, v2
	v_lshl_add_u64 v[60:61], v[60:61], 0, s[50:51]
	v_sub_u32_e32 v56, 0x7ff, v2
	v_lshl_add_u64 v[62:63], v[60:61], 0, v[22:23]
	v_cndmask_b32_e64 v60, v56, v2, s[0:1]
	v_ashrrev_i32_e32 v61, 31, v60
	v_lshl_add_u64 v[60:61], s[46:47], 0, v[60:61]
	v_mad_u64_u32 v[32:33], s[16:17], v60, s53, v[32:33]
	v_lshl_add_u64 v[0:1], v[34:35], 0, s[50:51]
	v_lshl_add_u64 v[34:35], v[34:35], 0, s[72:73]
	v_mad_i32_i24 v33, v61, s53, v33
	v_lshl_add_u64 v[34:35], v[34:35], 0, v[26:27]
	v_lshl_add_u64 v[60:61], v[32:33], 0, s[50:51]
	v_add_co_u32_e32 v34, vcc, s62, v34
	v_lshl_add_u64 v[64:65], v[60:61], 0, v[22:23]
	v_lshl_add_u64 v[60:61], v[32:33], 0, s[94:95]
	v_lshl_add_u64 v[0:1], v[0:1], 0, v[22:23]
	v_addc_co_u32_e32 v35, vcc, 0, v35, vcc
	v_lshl_add_u64 v[60:61], v[60:61], 0, s[50:51]
	v_lshl_add_u64 v[66:67], v[60:61], 0, v[22:23]
	global_load_dword v60, v[0:1], off offset:3136
	global_load_dword v61, v[62:63], off
	s_nop 0
	global_load_dwordx2 v[34:35], v[34:35], off offset:576
	s_nop 0
	global_load_dword v56, v[64:65], off offset:3136
	global_load_dword v58, v[66:67], off
	v_lshl_add_u64 v[0:1], v[32:33], 0, s[72:73]
	v_lshl_add_u64 v[0:1], v[0:1], 0, v[26:27]
	v_add_co_u32_e32 v0, vcc, 0x1000, v0
	s_cmp_lg_u32 s35, 0
	s_nop 0
	v_addc_co_u32_e32 v1, vcc, 0, v1, vcc
	global_load_dwordx2 v[32:33], v[0:1], off offset:576
	s_cselect_b64 s[16:17], -1, 0
	s_and_b64 s[18:19], s[4:5], s[16:17]
	s_and_saveexec_b64 s[16:17], s[18:19]
	s_cbranch_execz .LBB0_652
	s_sub_i32 s21, s20, 32
	s_sub_i32 vcc_lo, 0x7e0, s21
	s_cmp_lg_u64 s[0:1], 0
	s_cselect_b32 vcc_lo, s21, vcc_lo
	s_add_i32 vcc_lo, vcc_lo, s46
	s_lshl_b32 vcc_lo, vcc_lo, 11
	s_add_u32 s18, s68, vcc_lo
	s_addc_u32 s19, s69, 0
	v_add_u32_e32 v160, v45, v166
	v_add_u32_e32 v161, v44, v166
	ds_read_b64 v[162:163], v160
	ds_read_b64 v[164:165], v161
	s_waitcnt lgkmcnt(1)
	global_store_dwordx2 v167, v[162:163], s[18:19]
	s_waitcnt lgkmcnt(0)
	global_store_dwordx2 v168, v[164:165], s[18:19]

; template <int MODE>
; __device__ void scan_unit(int swave, const Params& p, int j, int b, int h, int dir, char* shm) {
;     ...
;   auto compute = [&](const char* buf, bf16_t* obuf) {
;     const bf16_t* qin = (const bf16_t*)buf; const bf16_t* ktil = (const bf16_t*)(buf + OFF_KT); const bf16_t* koutT = (const bf16_t*)(buf + OFF_KO);
;     const bf16_t* vT = (const bf16_t*)(buf + OFF_VT); const float* dec = (const float*)(buf + OFF_DEC);
;     bf16x8 Asc = {0, 0, 0, 0, 0, 0, 0, 0};
;     if (KS == 1 || wk == 0) {
;       f32x4 sc = {0.f, 0.f, 0.f, 0.f};
; #pragma unroll
;       for (int m = 0; m < DK / 32; ++m) {
;         const bf16x8 a = *(const bf16x8*)(ktil + r * QS + m * 32 + q4 * 8);
;         const bf16x8 bb = *(const bf16x8*)(qin + r * QS + m * 32 + q4 * 8);
;         sc = __builtin_amdgcn_mfma_f32_16x16x32_bf16(a, bb, sc, 0, 0, 0);
;       }
;       {
;         const unsigned p01 = pk2(q4 * 4 + 0 > r ? 0.f : sc[0], q4 * 4 + 1 > r ? 0.f : sc[1]);
;         const unsigned p23 = pk2(q4 * 4 + 2 > r ? 0.f : sc[2], q4 * 4 + 3 > r ? 0.f : sc[3]);
;         Asc[0] = (short)(p01 & 0xffff); Asc[1] = (short)(p01 >> 16); Asc[2] = (short)(p23 & 0xffff); Asc[3] = (short)(p23 >> 16);
;       }
;     }
;     bf16x8 Bv[NVT];
; #pragma unroll
;     for (int t = 0; t < NVT; ++t) {
;       const uint2 vv = *(const uint2*)(vT + ((vt0 + t) * 16 + r) * VS + q4 * 4);
;       Bv[t] = (bf16x8){(short)(vv.x & 0xffff), (short)(vv.x >> 16), (short)(vv.y & 0xffff), (short)(vv.y >> 16), 0, 0, 0, 0};
;     }
;     bf16x8 Aq[2];
; #pragma unroll
;     for (int m = 0; m < 2; ++m) {
;       const uint2 lo = *(const uint2*)(qin + r * QS + slab + (2 * m) * 16 + q4 * 4);
;       const uint2 hi = *(const uint2*)(qin + r * QS + slab + (2 * m + 1) * 16 + q4 * 4);
;       Aq[m] = (bf16x8){(short)(lo.x & 0xffff), (short)(lo.x >> 16), (short)(lo.y & 0xffff), (short)(lo.y >> 16),
;                        (short)(hi.x & 0xffff), (short)(hi.x >> 16), (short)(hi.y & 0xffff), (short)(hi.y >> 16)};
;     }
;     f32x4 o[NVT];
; #pragma unroll
;     for (int t = 0; t < NVT; ++t) {
;       o[t] = (f32x4){0.f, 0.f, 0.f, 0.f};
;       if (KS == 1 || wk == 0) o[t] = __builtin_amdgcn_mfma_f32_16x16x32_bf16(Asc, Bv[t], o[t], 0, 0, 0);
;     }
; #pragma unroll
;     for (int m = 0; m < 2; ++m)
; #pragma unroll
;       for (int t = 0; t < NVT; ++t) {
;         const f32x4 s0 = S[2 * m][t], s1 = S[2 * m + 1][t];
.LBB0_656:
	s_or_b64 exec, exec, s[16:17]
	ds_write_b16 v42, v28 offset:42752
	ds_write_b16_d16_hi v42, v28 offset:42792
	ds_write_b16 v42, v29 offset:42832
	ds_write_b16_d16_hi v42, v29 offset:42872
	ds_read_b128 v[28:31], v46 offset:2304
	ds_read_b128 v[62:65], v46
	ds_read_b128 v[66:69], v46 offset:2368
	ds_read_b128 v[70:73], v46 offset:64
	v_mov_b32_e32 v2, v3
	v_add_u32_e32 v54, 0x2800, v53
	s_waitcnt lgkmcnt(2)
	v_mfma_f32_16x16x32_bf16 v[28:31], v[28:31], v[62:65], 0
	ds_read_b64 v[62:63], v47 offset:6656
	ds_read2_b64 v[74:77], v53 offset1:4
	ds_read2_b64 v[78:81], v53 offset0:8 offset1:12
	v_mov_b32_e32 v64, v3
	v_mov_b32_e32 v65, v3
	s_waitcnt lgkmcnt(3)
	v_mfma_f32_16x16x32_bf16 v[28:31], v[66:69], v[70:73], v[28:31]
	s_waitcnt lgkmcnt(1)
	v_bfi_b32 v76, s30, v76, v76
	s_waitcnt lgkmcnt(0)
	v_bfi_b32 v80, s30, v80, v80
	v_cvt_pk_bf16_f32 v66, v16, v17
	v_cvt_pk_bf16_f32 v67, v18, v19
	v_cvt_pk_bf16_f32 v68, v12, v13
	s_nop 0
	v_cndmask_b32_e64 v0, v28, 0, s[6:7]
	v_cndmask_b32_e64 v1, 0, v29, s[8:9]
	v_cndmask_b32_e64 v28, v30, 0, s[10:11]
	v_cndmask_b32_e64 v29, v31, 0, s[12:13]
	v_cvt_pk_bf16_f32 v0, v0, v1
	v_cvt_pk_bf16_f32 v1, v28, v29
	v_cvt_pk_bf16_f32 v69, v14, v15
	s_nop 0
	v_mfma_f32_16x16x32_bf16 v[28:31], v[0:3], v[62:65], 0
	v_mfma_f32_16x16x32_bf16 v[28:31], v[74:77], v[66:69], v[28:31]
	v_cvt_pk_bf16_f32 v66, v8, v9
	v_cvt_pk_bf16_f32 v67, v10, v11
	v_cvt_pk_bf16_f32 v68, v4, v5
	v_cvt_pk_bf16_f32 v69, v6, v7
	s_nop 1
	v_mfma_f32_16x16x32_bf16 v[28:31], v[78:81], v[66:69], v[28:31]
	s_nop 7
	v_cvt_pk_bf16_f32 v0, v28, s0
	v_cvt_pk_bf16_f32 v1, v29, s0
	ds_write_b16 v48, v0 offset:48128
	ds_write_b16 v48, v1 offset:48392
	v_cvt_pk_bf16_f32 v0, v30, s0
	ds_write_b16 v48, v0 offset:48656
	v_cvt_pk_bf16_f32 v0, v31, s0
	ds_write_b16 v48, v0 offset:48920
	ds_read2st64_b64 v[28:31], v49 offset0:9 offset1:10
	ds_read2st64_b64 v[66:69], v49 offset0:11 offset1:12
	ds_read_b128 v[70:73], v50 offset:11776
	ds_read_b128 v[74:77], v50 offset:11840
	s_waitcnt lgkmcnt(3)
	s_waitcnt lgkmcnt(1)
	v_pk_mul_f32 v[18:19], v[18:19], v[72:73]
	v_pk_mul_f32 v[16:17], v[16:17], v[70:71]
	s_waitcnt lgkmcnt(0)
	v_pk_mul_f32 v[14:15], v[14:15], v[76:77]
	v_pk_mul_f32 v[12:13], v[12:13], v[74:75]
	v_mfma_f32_16x16x16_bf16 v[16:19], v[28:29], v[62:63], v[16:19]
	v_mov_b32_e32 v0, v30
	v_mov_b32_e32 v1, v31
	ds_read_b128 v[28:31], v50 offset:11904
	ds_read_b128 v[70:73], v50 offset:11968
	v_mfma_f32_16x16x16_bf16 v[12:15], v[0:1], v[62:63], v[12:15]
	s_waitcnt lgkmcnt(1)
	v_pk_mul_f32 v[10:11], v[10:11], v[30:31]
	v_pk_mul_f32 v[8:9], v[8:9], v[28:29]
	v_cvt_pk_bf16_f32 v74, v16, v17
	v_cvt_pk_bf16_f32 v75, v18, v19
	v_mfma_f32_16x16x16_bf16 v[28:31], v[66:67], v[62:63], v[8:11]
	s_nop 1
	v_cvt_pk_bf16_f32 v76, v12, v13
	ds_read_b128 v[8:11], v46 offset:14336
	s_waitcnt lgkmcnt(1)
	v_pk_mul_f32 v[6:7], v[6:7], v[72:73]
	v_pk_mul_f32 v[4:5], v[4:5], v[70:71]
	v_cvt_pk_bf16_f32 v77, v14, v15
	s_nop 0
	v_mfma_f32_16x16x16_bf16 v[4:7], v[68:69], v[62:63], v[4:7]
	ds_read_b128 v[62:65], v46 offset:14400
	ds_read_b128 v[66:69], v46 offset:12032
	ds_read_b128 v[70:73], v46 offset:12096
	s_waitcnt lgkmcnt(1)
	v_mfma_f32_16x16x32_bf16 v[8:11], v[8:11], v[66:69], 0
	v_mov_b32_e32 v68, v3
	v_mov_b32_e32 v69, v3
	s_waitcnt lgkmcnt(0)
	v_mfma_f32_16x16x32_bf16 v[8:11], v[62:65], v[70:73], v[8:11]
	s_nop 7
	v_cndmask_b32_e64 v0, v8, 0, s[6:7]
	v_cndmask_b32_e64 v1, 0, v9, s[8:9]
	v_cvt_pk_bf16_f32 v0, v0, v1
	v_cndmask_b32_e64 v1, v10, 0, s[10:11]
	v_cndmask_b32_e64 v2, v11, 0, s[12:13]
	ds_read2_b64 v[8:11], v54 offset0:224 offset1:228
	ds_read2_b64 v[62:65], v54 offset0:232 offset1:236
	v_cvt_pk_bf16_f32 v1, v1, v2
	ds_read_b64 v[66:67], v47 offset:18688
	v_mov_b32_e32 v2, v3
	s_waitcnt lgkmcnt(2)
	v_bfi_b32 v10, s30, v10, v10
	s_waitcnt lgkmcnt(1)
	v_bfi_b32 v64, s30, v64, v64
	s_waitcnt lgkmcnt(0)
	v_mfma_f32_16x16x32_bf16 v[70:73], v[0:3], v[66:69], 0
	v_mfma_f32_16x16x32_bf16 v[8:11], v[8:11], v[74:77], v[70:73]
	s_nop 6
	v_cvt_pk_bf16_f32 v70, v28, v29
	v_cvt_pk_bf16_f32 v71, v30, v31
	v_cvt_pk_bf16_f32 v72, v4, v5
	v_cvt_pk_bf16_f32 v73, v6, v7
	s_nop 1
	v_mfma_f32_16x16x32_bf16 v[8:11], v[62:65], v[70:73], v[8:11]
	v_add_u32_e32 v62, 0x100, v49
	s_nop 6
	v_cvt_pk_bf16_f32 v0, v8, s0
	ds_write_b16 v48, v0 offset:52352
	v_cvt_pk_bf16_f32 v0, v9, s0
	ds_write_b16 v48, v0 offset:52616
	v_cvt_pk_bf16_f32 v0, v10, s0
	ds_write_b16 v48, v0 offset:52880
	v_cvt_pk_bf16_f32 v0, v11, s0
	ds_write_b16 v48, v0 offset:53144
	ds_read2st64_b64 v[70:73], v62 offset0:32 offset1:33
	ds_read2st64_b64 v[74:77], v62 offset0:34 offset1:35
	ds_read_b128 v[8:11], v50 offset:23808
	ds_read_b128 v[78:81], v50 offset:23872
	s_waitcnt lgkmcnt(3)
	s_waitcnt lgkmcnt(1)
	v_pk_mul_f32 v[10:11], v[18:19], v[10:11]
	v_pk_mul_f32 v[8:9], v[16:17], v[8:9]
	s_waitcnt lgkmcnt(0)
	v_pk_mul_f32 v[14:15], v[14:15], v[80:81]
	v_pk_mul_f32 v[12:13], v[12:13], v[78:79]
	v_mfma_f32_16x16x16_bf16 v[8:11], v[70:71], v[66:67], v[8:11]
	v_mov_b32_e32 v0, v72
	v_mov_b32_e32 v1, v73
	ds_read_b128 v[16:19], v50 offset:23936
	ds_read_b128 v[70:73], v50 offset:24000
	v_mfma_f32_16x16x16_bf16 v[12:15], v[0:1], v[66:67], v[12:15]
	s_waitcnt lgkmcnt(1)
	v_pk_mul_f32 v[18:19], v[30:31], v[18:19]
	v_pk_mul_f32 v[16:17], v[28:29], v[16:17]
	s_waitcnt lgkmcnt(0)
	v_pk_mul_f32 v[6:7], v[6:7], v[72:73]
	v_pk_mul_f32 v[4:5], v[4:5], v[70:71]
	v_mfma_f32_16x16x16_bf16 v[16:19], v[74:75], v[66:67], v[16:19]
	s_waitcnt lgkmcnt(0)
	s_barrier
; __device__ __forceinline__ unsigned pk2(float lo, float hi) { f32x2_t v = {lo, hi}; bf16x2_t b = __builtin_convertvector(v, bf16x2_t); return __builtin_bit_cast(unsigned, b); }
; __device__ __forceinline__ float lo_bf(unsigned u) { return __uint_as_float(u << 16); }
; __device__ __forceinline__ float hi_bf(unsigned u) { return __uint_as_float(u & 0xffff0000u); }
; template <int MODE>
; __device__ void scan_unit(int swave, const Params& p, int j, int b, int h, int dir, char* shm) {
;     ...
;   auto load_raw = [&](int c, Raw& R) {
;     const int tok = tokof(c, ti);
;     const bf16_t* row = P + (rowbase + tok) * LDP;
;     if (MODE == 0) {
;       R.q = *(const unsigned*)(row + E_GQ + h * 64 + dp); R.k = *(const unsigned*)(row + E_GK + h * 64 + dp);
;       const uint4* lrp = (const uint4*)(row + (dir ? E_GLB : E_GLF));
;       R.lr0 = lrp[0]; R.lr1 = lrp[1];
;       R.v = *(const uint2*)(row + E_GV + h * 128 + vg * 4);
;     } else if (MODE == 1) {
;       R.q = *(const unsigned*)(row + E_HQ + h * 64 + dp); R.k = *(const unsigned*)(row + (dir ? E_HZB : E_HZF) + h * 64 + dp);
;       R.v = *(const uint2*)(row + E_HI + h * 128 + vg * 4);
;     } else {
;       R.q = *(const unsigned*)(row + O_RQ + h * 128 + dp); R.q2 = *(const unsigned*)(row + O_RQ + h * 128 + 64 + dp);
;       R.k = *(const unsigned*)(row + O_RK + h * 128 + dp); R.k2 = *(const unsigned*)(row + O_RK + h * 128 + 64 + dp);
;       R.cs = *(const float4*)(rope + tok * 64 + dp);
;       const unsigned* vp = (const unsigned*)(row + O_RV + h * 192 + vg * 6);
;       R.v30 = vp[0]; R.v31 = vp[1]; R.v32 = vp[2];
;     }
;   };
;     ...
;   auto ostore = [&](int c, const bf16_t* obuf) {
;     for (int idx = tid; idx < 16 * DV / 4; idx += 512) {
;       const int i = idx / (DV / 4), cc = (idx % (DV / 4)) * 4;
;       uint2 o = *(const uint2*)(obuf + i * OS + cc);
;       if (KS == 2) {
;         const uint2 o2 = *(const uint2*)(obuf + (16 + i) * OS + cc);
;         o.x = pk2(lo_bf(o.x) + lo_bf(o2.x), hi_bf(o.x) + hi_bf(o2.x)); o.y = pk2(lo_bf(o.y) + lo_bf(o2.y), hi_bf(o.y) + hi_bf(o2.y));
;       }
;       *(uint2*)(O + (rowbase + tokof(c, i)) * OLD + cc) = o;
;     }
	s_waitcnt vmcnt(3)
	s_waitcnt vmcnt(0)
	v_mfma_f32_16x16x16_bf16 v[4:7], v[76:77], v[66:67], v[4:7]
	s_add_i32 s16, s20, 0x60
	s_and_b64 s[2:3], s[2:3], exec
	s_cselect_b32 s2, s16, 0x7e0
	v_or_b32_e32 v2, s2, v37
	v_sub_u32_e32 v0, 0x7ff, v2
	v_cndmask_b32_e64 v0, v0, v2, s[0:1]
	v_or_b32_e32 v2, 16, v2
	v_ashrrev_i32_e32 v1, 31, v0
	v_sub_u32_e32 v57, 0x7ff, v2
	v_lshl_add_u64 v[0:1], s[46:47], 0, v[0:1]
	v_mov_b64_e32 v[28:29], s[48:49]
	v_cndmask_b32_e64 v64, v57, v2, s[0:1]
	v_mad_u64_u32 v[30:31], s[2:3], v0, s53, v[28:29]
	v_ashrrev_i32_e32 v65, 31, v64
	v_mad_i32_i24 v31, v1, s53, v31
	s_mov_b32 s71, s95
	v_lshl_add_u64 v[64:65], s[46:47], 0, v[64:65]
	v_lshl_add_u64 v[0:1], v[30:31], 0, s[50:51]
	v_lshl_add_u64 v[54:55], v[30:31], 0, s[94:95]
	v_lshl_add_u64 v[30:31], v[30:31], 0, s[70:71]
	v_mad_u64_u32 v[28:29], s[2:3], v64, s53, v[28:29]
	v_lshl_add_u64 v[30:31], v[30:31], 0, v[26:27]
	v_mad_i32_i24 v29, v65, s53, v29
	v_lshl_add_u64 v[54:55], v[54:55], 0, s[50:51]
	v_add_co_u32_e32 v30, vcc, s62, v30
	v_lshl_add_u64 v[66:67], v[28:29], 0, s[94:95]
	v_lshl_add_u64 v[0:1], v[0:1], 0, v[22:23]
	v_lshl_add_u64 v[54:55], v[54:55], 0, v[22:23]
	v_addc_co_u32_e32 v31, vcc, 0, v31, vcc
	v_lshl_add_u64 v[64:65], v[28:29], 0, s[50:51]
	v_lshl_add_u64 v[66:67], v[66:67], 0, s[50:51]
	v_lshl_add_u64 v[64:65], v[64:65], 0, v[22:23]
	v_lshl_add_u64 v[66:67], v[66:67], 0, v[22:23]
	global_load_dword v57, v[0:1], off offset:3136
	global_load_dword v59, v[54:55], off
	s_nop 0
	global_load_dwordx2 v[30:31], v[30:31], off offset:576
	s_nop 0
	global_load_dword v54, v[64:65], off offset:3136
	global_load_dword v55, v[66:67], off
	v_lshl_add_u64 v[0:1], v[28:29], 0, s[70:71]
	v_lshl_add_u64 v[0:1], v[0:1], 0, v[26:27]
	v_add_co_u32_e32 v0, vcc, 0x1000, v0
	s_nop 1
	v_addc_co_u32_e32 v1, vcc, 0, v1, vcc
	global_load_dwordx2 v[28:29], v[0:1], off offset:576
	s_and_saveexec_b64 s[2:3], s[4:5]
	s_cbranch_execz .LBB0_661
	s_sub_i32 vcc_lo, 0x7e0, s20
	s_cmp_lg_u64 s[0:1], 0
	s_cselect_b32 vcc_lo, s20, vcc_lo
	s_add_i32 vcc_lo, vcc_lo, s46
	s_lshl_b32 vcc_lo, vcc_lo, 11
	s_add_u32 s16, s68, vcc_lo
	s_addc_u32 s17, s69, 0
	v_add_u32_e32 v160, v51, v166
	v_add_u32_e32 v161, v52, v166
	ds_read_b64 v[162:163], v160
	ds_read_b64 v[164:165], v161
	s_waitcnt lgkmcnt(1)
	global_store_dwordx2 v167, v[162:163], s[16:17]
	s_waitcnt lgkmcnt(0)
	global_store_dwordx2 v168, v[164:165], s[16:17]

; template <int MODE>
; __device__ void scan_unit(int swave, const Params& p, int j, int b, int h, int dir, char* shm) {
;     ...
;   f32x4 S[4][NVT];
; #pragma unroll
;   for (int a = 0; a < 4; ++a)
; #pragma unroll
;     for (int t = 0; t < NVT; ++t) S[a][t] = (f32x4){0.f, 0.f, 0.f, 0.f};
;   auto compute = [&](const char* buf, bf16_t* obuf) {
;     const bf16_t* qin = (const bf16_t*)buf; const bf16_t* ktil = (const bf16_t*)(buf + OFF_KT); const bf16_t* koutT = (const bf16_t*)(buf + OFF_KO);
;     const bf16_t* vT = (const bf16_t*)(buf + OFF_VT); const float* dec = (const float*)(buf + OFF_DEC);
;     bf16x8 Asc = {0, 0, 0, 0, 0, 0, 0, 0};
;     if (KS == 1 || wk == 0) {
;       f32x4 sc = {0.f, 0.f, 0.f, 0.f};
; #pragma unroll
;       for (int m = 0; m < DK / 32; ++m) {
;         const bf16x8 a = *(const bf16x8*)(ktil + r * QS + m * 32 + q4 * 8);
;         const bf16x8 bb = *(const bf16x8*)(qin + r * QS + m * 32 + q4 * 8);
;         sc = __builtin_amdgcn_mfma_f32_16x16x32_bf16(a, bb, sc, 0, 0, 0);
;       }
;       {
;         const unsigned p01 = pk2(q4 * 4 + 0 > r ? 0.f : sc[0], q4 * 4 + 1 > r ? 0.f : sc[1]);
;         const unsigned p23 = pk2(q4 * 4 + 2 > r ? 0.f : sc[2], q4 * 4 + 3 > r ? 0.f : sc[3]);
;     ...
;   constexpr int NIT = NCH / 2, OB1 = KS * 16 * OS;
;   auto bufp = [&](int stage, int sub) { return buf0 + (stage * 2 + sub) * BUFB; };
;   auto obp = [&](int stage, int sub) { return obuf0 + (stage * 2 + sub) * OB1; };
;   Raw a0, a1, b0, b1;
;   __syncthreads();
;   load_raw(0, a0); load_raw(1, a1);
;   stage2(a0, bufp(0, 0), 0); stage2(a1, bufp(0, 1), 1);
;   load_raw(2, a0); load_raw(3, a1);
;   lds_barrier();
;   auto body = [&](int it, Raw& c0, Raw& c1, Raw& n0, Raw& n1) {
;     touch(c0); touch(c1);
;     __builtin_amdgcn_sched_barrier(0);
;     const int cA = 2 * it + 4 < NCH ? 2 * it + 4 : NCH - 2;
;     load_raw(cA, n0); load_raw(cA + 1, n1);
;     if (it > 0) { ostore(2 * it - 2, obp((it - 1) & 1, 0)); ostore(2 * it - 1, obp((it - 1) & 1, 1)); }
;     stage2(c0, bufp((it + 1) & 1, 0), 0); stage2(c1, bufp((it + 1) & 1, 1), 0);
;     compute(bufp(it & 1, 0), obp(it & 1, 0)); compute(bufp(it & 1, 1), obp(it & 1, 1));
;     lds_barrier();
;   };
;   for (int it = 0; it < NIT; it += 2) { body(it, a0, a1, b0, b1); body(it + 1, b0, b1, a0, a1); }
.LBB0_675:
	s_or_b64 exec, exec, s[4:5]
	v_readlane_b32 s8, v248, 8
	v_readlane_b32 s10, v248, 10
	v_readlane_b32 s11, v248, 11
	s_add_u32 s4, s10, s2
	s_addc_u32 s5, s11, s3
	s_and_b64 s[2:3], s[0:1], exec
	s_cselect_b32 s2, 0, 0x4000000
	s_add_u32 s2, s4, s2
	s_addc_u32 s3, s5, 0
	s_lshl_b32 s50, s94, 1
	s_add_u32 s2, s2, s50
	v_or_b32_e32 v4, 32, v99
	v_xor_b32_e32 v5, 0x7df, v99
	s_addc_u32 s3, s3, 0
	v_cndmask_b32_e64 v4, v5, v4, s[0:1]
	s_add_u32 s48, s2, 0x4000000
	v_or_b32_e32 v6, s18, v4
	v_mov_b64_e32 v[4:5], s[46:47]
	s_addc_u32 s49, s3, 0
	v_mad_u64_u32 v[6:7], s[2:3], v6, s53, v[4:5]
	s_mov_b32 s68, s50
	s_mov_b32 s69, s95
	v_mad_i32_i24 v7, s19, v156, v7
	s_lshl_b32 s94, s6, 1
	s_mov_b32 s70, s44
	s_mov_b32 s71, s95
	v_lshl_add_u64 v[8:9], v[6:7], 0, s[94:95]
	v_lshl_add_u64 v[10:11], v[6:7], 0, s[70:71]
	v_lshl_add_u64 v[6:7], v[6:7], 0, s[68:69]
	v_lshl_add_u64 v[8:9], v[8:9], 0, v[82:83]
	v_lshl_add_u64 v[6:7], v[6:7], 0, v[84:85]
	global_load_dword v119, v[8:9], off
	global_load_dword v118, v[8:9], off offset:512
	global_load_dwordx4 v[16:19], v[10:11], off
	global_load_dwordx4 v[12:15], v[10:11], off offset:16
	global_load_dwordx2 v[94:95], v[6:7], off offset:1024
	v_or_b32_e32 v6, 48, v99
	v_xor_b32_e32 v7, 0x7cf, v99
	v_cndmask_b32_e64 v6, v7, v6, s[0:1]
	v_or_b32_e32 v6, s18, v6
	v_mad_u64_u32 v[4:5], s[2:3], v6, s53, v[4:5]
	v_mad_i32_i24 v5, s19, v156, v5
	v_lshl_add_u64 v[6:7], v[4:5], 0, s[94:95]
	v_lshl_add_u64 v[6:7], v[6:7], 0, v[82:83]
	v_lshl_add_u64 v[22:23], v[4:5], 0, s[70:71]
	global_load_dword v117, v[6:7], off
	global_load_dword v116, v[6:7], off offset:512
	global_load_dwordx4 v[8:11], v[22:23], off
	v_lshl_add_u64 v[4:5], v[4:5], 0, s[68:69]
	v_lshl_add_u64 v[24:25], v[4:5], 0, v[84:85]
	global_load_dwordx4 v[4:7], v[22:23], off offset:16
	global_load_dwordx2 v[90:91], v[24:25], off offset:1024
	v_lshrrev_b32_e32 v21, 4, v2
	v_readlane_b32 s9, v248, 9
	s_waitcnt vmcnt(10)
	ds_write_b16 v104, v0 offset:18688
	ds_write_b16_d16_hi v104, v0 offset:18728
	ds_write_b16 v104, v1 offset:18768
	ds_write_b16_d16_hi v104, v1 offset:18808
	v_and_b32_e32 v1, 48, v2
	v_lshlrev_b32_e32 v2, 2, v21
	v_add_u32_e32 v108, v20, v1
	v_cmp_gt_u32_e64 s[6:7], v2, v99
	v_cmp_lt_u32_e64 s[8:9], v2, v99
	v_or_b32_e32 v20, 2, v2
	v_or_b32_e32 v2, 3, v2
	s_movk_i32 s2, 0x200
	v_cmp_gt_u32_e64 s[12:13], v2, v99
	v_ashrrev_i32_e32 v2, 2, v98
	v_cmp_gt_i32_e64 s[4:5], s2, v98
	v_and_or_b32 v2, v2, -16, v99
	s_movk_i32 s2, 0x210
	v_cmp_gt_u32_e64 s[10:11], v20, v99
	v_mul_lo_u32 v20, v2, 40
	v_mad_u32_u24 v2, v21, s2, v2
	v_lshlrev_b32_e32 v0, 3, v21
	v_lshl_add_u32 v110, v2, 1, 0
	v_lshlrev_b32_e32 v2, 5, v99
	v_add3_u32 v109, 0, v20, v0
	v_sub_u32_e32 v20, 0, v0
	v_add3_u32 v111, 0, v2, v0
	v_lshlrev_b32_e32 v0, 3, v98
	v_readlane_b32 s2, v247, 39
	s_waitcnt lgkmcnt(0)
	s_barrier
	v_mov_b32_e32 v36, 0
	v_add_u32_e32 v107, s2, v0
	v_readlane_b32 s2, v247, 40
	s_mov_b32 s35, 0
	v_add_u32_e32 v112, 0, v1
	v_add_u32_e32 v106, s2, v0
	v_readlane_b32 s2, v247, 41
	v_lshlrev_b32_e32 v105, 2, v98
	v_add_u32_e32 v115, v108, v20
	v_add_u32_e32 v113, s2, v0
	v_readlane_b32 s2, v247, 42
	v_mov_b32_e32 v37, v36
	v_mov_b32_e32 v38, v36
	v_add_u32_e32 v114, s2, v0
	v_mov_b32_e32 v39, v36
	v_mov_b32_e32 v40, v36
	v_mov_b32_e32 v41, v36
	v_mov_b32_e32 v42, v36
	v_mov_b32_e32 v43, v36
	v_mov_b32_e32 v44, v36
	v_mov_b32_e32 v45, v36
	v_mov_b32_e32 v46, v36
	v_mov_b32_e32 v47, v36
	v_mov_b32_e32 v48, v36
	v_mov_b32_e32 v49, v36
	v_mov_b32_e32 v50, v36
	v_mov_b32_e32 v51, v36
	v_lshrrev_b32_e32 v166, 5, v147
	v_sub_u32_e32 v167, 15, v166
	v_cndmask_b32_e64 v167, v167, v166, s[0:1]
	v_lshlrev_b32_e32 v167, 11, v167
	v_and_b32_e32 v168, 31, v147
	v_lshl_add_u32 v167, v168, 3, v167
	v_add_u32_e32 v168, 0x8000, v167
	v_cndmask_b32_e64 v169, v168, v167, s[0:1]
	v_cndmask_b32_e64 v168, v167, v168, s[0:1]
	v_mov_b32_e32 v167, v169
	v_lshlrev_b32_e32 v166, 3, v166
	s_branch .LBB0_677
.LBB0_676:
	s_or_b64 exec, exec, s[2:3]
	ds_write_b16 v104, v92 offset:18688
	ds_write_b16_d16_hi v104, v92 offset:18728
	ds_write_b16 v104, v93 offset:18768
	ds_write_b16_d16_hi v104, v93 offset:18808
	ds_read_b128 v[20:23], v108 offset:26368
	ds_read_b128 v[24:27], v108 offset:24064
	ds_read_b128 v[28:31], v108 offset:26432
	ds_read_b128 v[32:35], v108 offset:24128
	v_add_u32_e32 v0, 0x5800, v115
	s_add_i32 s35, s35, 2
	s_waitcnt lgkmcnt(2)
	v_mfma_f32_16x16x32_bf16 v[20:23], v[20:23], v[24:27], 0
	ds_read_b64 v[24:25], v109 offset:30720
	ds_read2_b64 v[120:123], v0 offset0:192 offset1:196
	ds_read2_b64 v[126:129], v0 offset0:200 offset1:204
	v_mov_b32_e32 v26, v3
	v_mov_b32_e32 v27, v3
	s_waitcnt lgkmcnt(3)
	v_mfma_f32_16x16x32_bf16 v[20:23], v[28:31], v[32:35], v[20:23]
	s_waitcnt lgkmcnt(1)
	v_bfi_b32 v122, s30, v122, v122
	s_waitcnt lgkmcnt(0)
	v_bfi_b32 v128, s30, v128, v128
	v_cvt_pk_bf16_f32 v28, v40, v41
	v_cvt_pk_bf16_f32 v29, v42, v43
	v_cvt_pk_bf16_f32 v30, v44, v45
	s_nop 0
	v_cndmask_b32_e64 v0, v20, 0, s[6:7]
	v_cndmask_b32_e64 v1, 0, v21, s[8:9]
	v_cndmask_b32_e64 v2, v22, 0, s[10:11]
	v_cndmask_b32_e64 v20, v23, 0, s[12:13]
	v_cvt_pk_bf16_f32 v0, v0, v1
	v_cvt_pk_bf16_f32 v1, v2, v20
	v_mov_b32_e32 v2, v3
	v_cvt_pk_bf16_f32 v31, v46, v47
	s_and_b64 vcc, exec, s[72:73]
	v_mfma_f32_16x16x32_bf16 v[20:23], v[0:3], v[24:27], 0
	v_mfma_f32_16x16x32_bf16 v[20:23], v[120:123], v[28:31], v[20:23]
	v_cvt_pk_bf16_f32 v28, v48, v49
	v_cvt_pk_bf16_f32 v29, v50, v51
	v_cvt_pk_bf16_f32 v30, v36, v37
	v_cvt_pk_bf16_f32 v31, v38, v39
	s_nop 1
	v_mfma_f32_16x16x32_bf16 v[20:23], v[126:129], v[28:31], v[20:23]
	s_nop 7
	v_cvt_pk_bf16_f32 v0, v20, s0
	ds_write_b16 v110, v0 offset:56576
	v_cvt_pk_bf16_f32 v0, v21, s0
	ds_write_b16 v110, v0 offset:56840
	v_cvt_pk_bf16_f32 v0, v22, s0
	ds_write_b16 v110, v0 offset:57104
	v_cvt_pk_bf16_f32 v0, v23, s0
	ds_write_b16 v110, v0 offset:57368
	ds_read2st64_b64 v[20:23], v111 offset0:56 offset1:57
	ds_read2st64_b64 v[28:31], v111 offset0:58 offset1:59
	ds_read_b128 v[32:35], v112 offset:35840
	ds_read_b128 v[120:123], v112 offset:35904
	s_waitcnt lgkmcnt(3)
; __device__ __forceinline__ float lo_bf(unsigned u) { return __uint_as_float(u << 16); }
; template <int MODE>
; __device__ void scan_unit(int swave, const Params& p, int j, int b, int h, int dir, char* shm) {
;     ...
;   auto load_raw = [&](int c, Raw& R) {
;     const int tok = tokof(c, ti);
;     const bf16_t* row = P + (rowbase + tok) * LDP;
;     if (MODE == 0) {
;       R.q = *(const unsigned*)(row + E_GQ + h * 64 + dp); R.k = *(const unsigned*)(row + E_GK + h * 64 + dp);
;       const uint4* lrp = (const uint4*)(row + (dir ? E_GLB : E_GLF));
;       R.lr0 = lrp[0]; R.lr1 = lrp[1];
;       R.v = *(const uint2*)(row + E_GV + h * 128 + vg * 4);
;     } else if (MODE == 1) {
;       R.q = *(const unsigned*)(row + E_HQ + h * 64 + dp); R.k = *(const unsigned*)(row + (dir ? E_HZB : E_HZF) + h * 64 + dp);
;       R.v = *(const uint2*)(row + E_HI + h * 128 + vg * 4);
;     } else {
;       R.q = *(const unsigned*)(row + O_RQ + h * 128 + dp); R.q2 = *(const unsigned*)(row + O_RQ + h * 128 + 64 + dp);
;       R.k = *(const unsigned*)(row + O_RK + h * 128 + dp); R.k2 = *(const unsigned*)(row + O_RK + h * 128 + 64 + dp);
;       R.cs = *(const float4*)(rope + tok * 64 + dp);
;       const unsigned* vp = (const unsigned*)(row + O_RV + h * 192 + vg * 6);
;       R.v30 = vp[0]; R.v31 = vp[1]; R.v32 = vp[2];
;     }
;   };
;     ...
;     for (int kt = 0; kt < 4; ++kt) {
;       const uint2 kk = *(const uint2*)(koutT + (slab + kt * 16 + r) * 16 + q4 * 4);
;       const bf16x8 Ak = {(short)(kk.x & 0xffff), (short)(kk.x >> 16), (short)(kk.y & 0xffff), (short)(kk.y >> 16), 0, 0, 0, 0};
;       const f32x4 dc = *(const f32x4*)(dec + slab + kt * 16 + q4 * 4);
; #pragma unroll
;       for (int t = 0; t < NVT; ++t) S[kt][t] = __builtin_amdgcn_mfma_f32_16x16x32_bf16(Ak, Bv[t], S[kt][t] * dc, 0, 0, 0);
;     }
;   };
;   auto ostore = [&](int c, const bf16_t* obuf) {
;     for (int idx = tid; idx < 16 * DV / 4; idx += 512) {
;       const int i = idx / (DV / 4), cc = (idx % (DV / 4)) * 4;
;       uint2 o = *(const uint2*)(obuf + i * OS + cc);
;       if (KS == 2) {
;         const uint2 o2 = *(const uint2*)(obuf + (16 + i) * OS + cc);
;         o.x = pk2(lo_bf(o.x) + lo_bf(o2.x), hi_bf(o.x) + hi_bf(o2.x)); o.y = pk2(lo_bf(o.y) + lo_bf(o2.y), hi_bf(o.y) + hi_bf(o2.y));
;       }
;       *(uint2*)(O + (rowbase + tokof(c, i)) * OLD + cc) = o;
;     }
	v_mov_b32_e32 v0, v20
	v_mov_b32_e32 v1, v21
	s_waitcnt lgkmcnt(1)
	v_pk_mul_f32 v[34:35], v[42:43], v[34:35]
	v_pk_mul_f32 v[32:33], v[40:41], v[32:33]
	s_waitcnt lgkmcnt(0)
	v_pk_mul_f32 v[20:21], v[44:45], v[120:121]
	ds_read_b128 v[40:43], v112 offset:35968
	v_mfma_f32_16x16x16_bf16 v[32:35], v[0:1], v[24:25], v[32:35]
	v_mov_b32_e32 v0, v22
	v_mov_b32_e32 v1, v23
	v_pk_mul_f32 v[22:23], v[46:47], v[122:123]
	ds_read_b128 v[44:47], v112 offset:36032
	s_waitcnt lgkmcnt(1)
	v_pk_mul_f32 v[42:43], v[50:51], v[42:43]
	v_mfma_f32_16x16x16_bf16 v[20:23], v[0:1], v[24:25], v[20:23]
	v_pk_mul_f32 v[40:41], v[48:49], v[40:41]
	v_mov_b32_e32 v122, v3
	v_mov_b32_e32 v123, v3
	v_mfma_f32_16x16x16_bf16 v[40:43], v[28:29], v[24:25], v[40:43]
	v_mov_b32_e32 v0, v30
	v_mov_b32_e32 v1, v31
	ds_read_b128 v[28:31], v108 offset:38400
	s_waitcnt lgkmcnt(1)
	v_pk_mul_f32 v[38:39], v[38:39], v[46:47]
	v_pk_mul_f32 v[36:37], v[36:37], v[44:45]
	s_nop 1
	v_mfma_f32_16x16x16_bf16 v[24:27], v[0:1], v[24:25], v[36:39]
	s_nop 2
	ds_read_b128 v[36:39], v108 offset:38464
	ds_read_b128 v[44:47], v108 offset:36096
	ds_read_b128 v[48:51], v108 offset:36160
	s_waitcnt lgkmcnt(1)
	v_mfma_f32_16x16x32_bf16 v[28:31], v[28:31], v[44:47], 0
	s_waitcnt lgkmcnt(0)
	v_mfma_f32_16x16x32_bf16 v[28:31], v[36:39], v[48:51], v[28:31]
	v_add_u32_e32 v36, 0x8800, v115
	v_cvt_pk_bf16_f32 v48, v32, v33
	v_cvt_pk_bf16_f32 v49, v34, v35
	v_cvt_pk_bf16_f32 v50, v20, v21
	v_cvt_pk_bf16_f32 v51, v22, v23
	s_nop 2
	v_cndmask_b32_e64 v0, v28, 0, s[6:7]
	v_cndmask_b32_e64 v1, 0, v29, s[8:9]
	v_cvt_pk_bf16_f32 v0, v0, v1
	v_cndmask_b32_e64 v1, v30, 0, s[10:11]
	v_cndmask_b32_e64 v2, v31, 0, s[12:13]
	ds_read2_b64 v[28:31], v36 offset0:160 offset1:164
	ds_read2_b64 v[36:39], v36 offset0:168 offset1:172
	v_cvt_pk_bf16_f32 v1, v1, v2
	ds_read_b64 v[120:121], v109 offset:42752
	v_mov_b32_e32 v2, v3
	s_waitcnt lgkmcnt(2)
	v_bfi_b32 v30, s30, v30, v30
	s_waitcnt lgkmcnt(1)
	v_bfi_b32 v38, s30, v38, v38
	s_waitcnt lgkmcnt(0)
	v_mfma_f32_16x16x32_bf16 v[44:47], v[0:3], v[120:123], 0
	v_mfma_f32_16x16x32_bf16 v[28:31], v[28:31], v[48:51], v[44:47]
	s_nop 6
	v_cvt_pk_bf16_f32 v44, v40, v41
	v_cvt_pk_bf16_f32 v45, v42, v43
	v_cvt_pk_bf16_f32 v46, v24, v25
	v_cvt_pk_bf16_f32 v47, v26, v27
	s_nop 1
	v_mfma_f32_16x16x32_bf16 v[28:31], v[36:39], v[44:47], v[28:31]
	s_nop 7
	v_cvt_pk_bf16_f32 v0, v28, s0
	ds_write_b16 v110, v0 offset:60800
	v_cvt_pk_bf16_f32 v0, v29, s0
	ds_write_b16 v110, v0 offset:61064
	v_cvt_pk_bf16_f32 v0, v30, s0
	ds_write_b16 v110, v0 offset:61328
	v_cvt_pk_bf16_f32 v0, v31, s0
	ds_write_b16 v110, v0 offset:61592
	ds_read2st64_b64 v[28:31], v124 offset0:79 offset1:80
	ds_read2st64_b64 v[36:39], v124 offset0:81 offset1:82
	ds_read_b128 v[44:47], v112 offset:47872
	ds_read_b128 v[124:127], v112 offset:47936
	s_waitcnt lgkmcnt(3)
	s_waitcnt lgkmcnt(1)
	v_pk_mul_f32 v[34:35], v[34:35], v[46:47]
	v_pk_mul_f32 v[32:33], v[32:33], v[44:45]
	s_waitcnt lgkmcnt(0)
	v_pk_mul_f32 v[22:23], v[22:23], v[126:127]
	v_pk_mul_f32 v[20:21], v[20:21], v[124:125]
	v_mfma_f32_16x16x16_bf16 v[48:51], v[28:29], v[120:121], v[32:35]
	v_mov_b32_e32 v0, v30
	v_mov_b32_e32 v1, v31
	ds_read_b128 v[28:31], v112 offset:48064
	s_nop 0
	v_mfma_f32_16x16x16_bf16 v[44:47], v[0:1], v[120:121], v[20:23]
	s_nop 1
	ds_read_b128 v[20:23], v112 offset:48000
	s_waitcnt lgkmcnt(0)
	s_barrier
	s_waitcnt lgkmcnt(0)
	v_pk_mul_f32 v[22:23], v[42:43], v[22:23]
	v_pk_mul_f32 v[20:21], v[40:41], v[20:21]
	s_nop 1
	v_mfma_f32_16x16x16_bf16 v[40:43], v[36:37], v[120:121], v[20:23]
	v_mov_b32_e32 v0, v38
	v_mov_b32_e32 v1, v39
	s_nop 0
	v_pk_mul_f32 v[22:23], v[26:27], v[30:31]
	v_pk_mul_f32 v[20:21], v[24:25], v[28:29]
	s_nop 1
	v_mfma_f32_16x16x16_bf16 v[36:39], v[0:1], v[120:121], v[20:23]
	s_cbranch_vccnz .LBB0_695
.LBB0_677:
	s_waitcnt vmcnt(5)
	s_waitcnt vmcnt(0)
	s_cmp_gt_u32 s35, 61
	s_cselect_b64 s[72:73], -1, 0
	s_lshl_b32 s28, s35, 5
	s_add_i32 s20, s28, 64
	s_cmp_lt_u32 s35, 62
	s_cselect_b64 s[2:3], -1, 0
	s_and_b64 s[16:17], s[2:3], exec
	s_cselect_b32 s16, s20, 0x7e0
	v_or_b32_e32 v2, s16, v99
	v_sub_u32_e32 v0, 0x7ff, v2
	v_cndmask_b32_e64 v0, v0, v2, s[0:1]
	v_ashrrev_i32_e32 v1, 31, v0
	v_lshl_add_u64 v[0:1], s[18:19], 0, v[0:1]
	v_mov_b64_e32 v[20:21], s[46:47]
	v_mad_u64_u32 v[22:23], s[16:17], v0, s53, v[20:21]
	v_mad_i32_i24 v23, v1, s53, v23
	v_lshl_add_u64 v[0:1], v[22:23], 0, s[94:95]
	v_lshl_add_u64 v[0:1], v[0:1], 0, v[82:83]
	v_lshl_add_u64 v[24:25], v[22:23], 0, s[70:71]
	global_load_dword v123, v[0:1], off
	global_load_dword v122, v[0:1], off offset:512
	global_load_dwordx4 v[32:35], v[24:25], off
	v_lshl_add_u64 v[0:1], v[22:23], 0, s[68:69]
	v_lshl_add_u64 v[0:1], v[0:1], 0, v[84:85]
	global_load_dwordx4 v[28:31], v[24:25], off offset:16
	global_load_dwordx2 v[96:97], v[0:1], off offset:1024
	v_or_b32_e32 v0, 16, v2
	v_sub_u32_e32 v1, 0x7ff, v0
	v_cndmask_b32_e64 v0, v1, v0, s[0:1]
	v_ashrrev_i32_e32 v1, 31, v0
	v_lshl_add_u64 v[0:1], s[18:19], 0, v[0:1]
	v_mad_u64_u32 v[20:21], s[16:17], v0, s53, v[20:21]
	v_mad_i32_i24 v21, v1, s53, v21
	v_lshl_add_u64 v[0:1], v[20:21], 0, s[94:95]
	v_lshl_add_u64 v[0:1], v[0:1], 0, v[82:83]
	v_lshl_add_u64 v[22:23], v[20:21], 0, s[70:71]
	global_load_dword v121, v[0:1], off
	global_load_dword v120, v[0:1], off offset:512
	global_load_dwordx4 v[24:27], v[22:23], off
	v_lshl_add_u64 v[0:1], v[20:21], 0, s[68:69]
	v_lshl_add_u64 v[0:1], v[0:1], 0, v[84:85]
	global_load_dwordx4 v[20:23], v[22:23], off offset:16
	s_nop 0
	global_load_dwordx2 v[92:93], v[0:1], off offset:1024
	s_cmp_lg_u32 s35, 0
	s_cselect_b64 s[16:17], -1, 0
	s_and_b64 s[20:21], s[4:5], s[16:17]
	s_and_saveexec_b64 s[16:17], s[20:21]
	s_cbranch_execz .LBB0_682
	s_sub_i32 s20, s28, 32
	s_sub_i32 vcc_lo, 0x7e0, s20
	s_cmp_lg_u64 s[0:1], 0
	s_cselect_b32 vcc_lo, s20, vcc_lo
	s_add_i32 vcc_lo, vcc_lo, s18
	s_lshl_b32 vcc_lo, vcc_lo, 11
	s_add_u32 s24, s48, vcc_lo
	s_addc_u32 s25, s49, 0
	v_add_u32_e32 v160, v107, v166
	v_add_u32_e32 v161, v106, v166
	ds_read_b64 v[162:163], v160
	ds_read_b64 v[164:165], v161
	s_waitcnt lgkmcnt(1)
	global_store_dwordx2 v167, v[162:163], s[24:25]
	s_waitcnt lgkmcnt(0)
	global_store_dwordx2 v168, v[164:165], s[24:25]

; template <int MODE>
; __device__ void scan_unit(int swave, const Params& p, int j, int b, int h, int dir, char* shm) {
;     ...
;   auto compute = [&](const char* buf, bf16_t* obuf) {
;     const bf16_t* qin = (const bf16_t*)buf; const bf16_t* ktil = (const bf16_t*)(buf + OFF_KT); const bf16_t* koutT = (const bf16_t*)(buf + OFF_KO);
;     const bf16_t* vT = (const bf16_t*)(buf + OFF_VT); const float* dec = (const float*)(buf + OFF_DEC);
;     bf16x8 Asc = {0, 0, 0, 0, 0, 0, 0, 0};
;     if (KS == 1 || wk == 0) {
;       f32x4 sc = {0.f, 0.f, 0.f, 0.f};
; #pragma unroll
;       for (int m = 0; m < DK / 32; ++m) {
;         const bf16x8 a = *(const bf16x8*)(ktil + r * QS + m * 32 + q4 * 8);
;         const bf16x8 bb = *(const bf16x8*)(qin + r * QS + m * 32 + q4 * 8);
;         sc = __builtin_amdgcn_mfma_f32_16x16x32_bf16(a, bb, sc, 0, 0, 0);
;       }
;       {
;         const unsigned p01 = pk2(q4 * 4 + 0 > r ? 0.f : sc[0], q4 * 4 + 1 > r ? 0.f : sc[1]);
;         const unsigned p23 = pk2(q4 * 4 + 2 > r ? 0.f : sc[2], q4 * 4 + 3 > r ? 0.f : sc[3]);
;         Asc[0] = (short)(p01 & 0xffff); Asc[1] = (short)(p01 >> 16); Asc[2] = (short)(p23 & 0xffff); Asc[3] = (short)(p23 >> 16);
;       }
;     }
;     bf16x8 Bv[NVT];
; #pragma unroll
;     for (int t = 0; t < NVT; ++t) {
;       const uint2 vv = *(const uint2*)(vT + ((vt0 + t) * 16 + r) * VS + q4 * 4);
;       Bv[t] = (bf16x8){(short)(vv.x & 0xffff), (short)(vv.x >> 16), (short)(vv.y & 0xffff), (short)(vv.y >> 16), 0, 0, 0, 0};
;     }
;     bf16x8 Aq[2];
; #pragma unroll
;     for (int m = 0; m < 2; ++m) {
;       const uint2 lo = *(const uint2*)(qin + r * QS + slab + (2 * m) * 16 + q4 * 4);
;       const uint2 hi = *(const uint2*)(qin + r * QS + slab + (2 * m + 1) * 16 + q4 * 4);
;       Aq[m] = (bf16x8){(short)(lo.x & 0xffff), (short)(lo.x >> 16), (short)(lo.y & 0xffff), (short)(lo.y >> 16),
;                        (short)(hi.x & 0xffff), (short)(hi.x >> 16), (short)(hi.y & 0xffff), (short)(hi.y >> 16)};
;     }
;     f32x4 o[NVT];
; #pragma unroll
;     for (int t = 0; t < NVT; ++t) {
;       o[t] = (f32x4){0.f, 0.f, 0.f, 0.f};
;       if (KS == 1 || wk == 0) o[t] = __builtin_amdgcn_mfma_f32_16x16x32_bf16(Asc, Bv[t], o[t], 0, 0, 0);
;     }
; #pragma unroll
;     for (int m = 0; m < 2; ++m)
; #pragma unroll
;       for (int t = 0; t < NVT; ++t) {
;         const f32x4 s0 = S[2 * m][t], s1 = S[2 * m + 1][t];
.LBB0_686:
	s_or_b64 exec, exec, s[16:17]
	ds_write_b16 v104, v90 offset:42752
	ds_write_b16_d16_hi v104, v90 offset:42792
	ds_write_b16 v104, v91 offset:42832
	ds_write_b16_d16_hi v104, v91 offset:42872
	ds_read_b128 v[4:7], v108 offset:2304
	ds_read_b128 v[8:11], v108
	ds_read_b128 v[12:15], v108 offset:2368
	ds_read_b128 v[16:19], v108 offset:64
	v_mov_b32_e32 v2, v3
	v_mov_b32_e32 v128, v3
	s_waitcnt lgkmcnt(2)
	v_mfma_f32_16x16x32_bf16 v[4:7], v[4:7], v[8:11], 0
	ds_read_b64 v[8:9], v109 offset:6656
	ds_read2_b64 v[116:119], v115 offset1:4
	ds_read2_b64 v[124:127], v115 offset0:8 offset1:12
	v_mov_b32_e32 v10, v3
	v_mov_b32_e32 v11, v3
	s_waitcnt lgkmcnt(3)
	v_mfma_f32_16x16x32_bf16 v[4:7], v[12:15], v[16:19], v[4:7]
	s_waitcnt lgkmcnt(1)
	v_bfi_b32 v118, s30, v118, v118
	s_waitcnt lgkmcnt(0)
	v_bfi_b32 v126, s30, v126, v126
	v_cvt_pk_bf16_f32 v12, v48, v49
	v_cvt_pk_bf16_f32 v13, v50, v51
	v_cvt_pk_bf16_f32 v14, v44, v45
	s_nop 0
	v_cndmask_b32_e64 v0, v4, 0, s[6:7]
	v_cndmask_b32_e64 v1, 0, v5, s[8:9]
	v_cndmask_b32_e64 v4, v6, 0, s[10:11]
	v_cndmask_b32_e64 v5, v7, 0, s[12:13]
	v_cvt_pk_bf16_f32 v0, v0, v1
	v_cvt_pk_bf16_f32 v1, v4, v5
	v_cvt_pk_bf16_f32 v15, v46, v47
	v_mov_b32_e32 v129, v3
	v_mfma_f32_16x16x32_bf16 v[4:7], v[0:3], v[8:11], 0
	v_mfma_f32_16x16x32_bf16 v[4:7], v[116:119], v[12:15], v[4:7]
	v_cvt_pk_bf16_f32 v12, v40, v41
	v_cvt_pk_bf16_f32 v13, v42, v43
	v_cvt_pk_bf16_f32 v14, v36, v37
	v_cvt_pk_bf16_f32 v15, v38, v39
	s_nop 1
	v_mfma_f32_16x16x32_bf16 v[4:7], v[124:127], v[12:15], v[4:7]
	v_add_u32_e32 v124, 0x100, v111
	s_nop 6
	v_cvt_pk_bf16_f32 v0, v4, s0
	v_cvt_pk_bf16_f32 v1, v5, s0
	ds_write_b16 v110, v0 offset:48128
	ds_write_b16 v110, v1 offset:48392
	v_cvt_pk_bf16_f32 v0, v6, s0
	ds_write_b16 v110, v0 offset:48656
	v_cvt_pk_bf16_f32 v0, v7, s0
	ds_write_b16 v110, v0 offset:48920
	ds_read2st64_b64 v[4:7], v111 offset0:9 offset1:10
	ds_read2st64_b64 v[12:15], v111 offset0:11 offset1:12
	ds_read_b128 v[16:19], v112 offset:11776
	ds_read_b128 v[116:119], v112 offset:11840
	s_waitcnt lgkmcnt(3)
	v_mov_b32_e32 v0, v4
	v_mov_b32_e32 v1, v5
	s_waitcnt lgkmcnt(1)
	v_pk_mul_f32 v[18:19], v[50:51], v[18:19]
	v_pk_mul_f32 v[16:17], v[48:49], v[16:17]
	s_waitcnt lgkmcnt(0)
	v_pk_mul_f32 v[4:5], v[44:45], v[116:117]
	ds_read_b128 v[48:51], v112 offset:11968
	v_mfma_f32_16x16x16_bf16 v[16:19], v[0:1], v[8:9], v[16:19]
	v_mov_b32_e32 v0, v6
	v_mov_b32_e32 v1, v7
	v_pk_mul_f32 v[6:7], v[46:47], v[118:119]
	ds_read_b128 v[44:47], v112 offset:11904
	s_waitcnt lgkmcnt(0)
	v_pk_mul_f32 v[42:43], v[42:43], v[46:47]
	v_mfma_f32_16x16x16_bf16 v[4:7], v[0:1], v[8:9], v[4:7]
	v_pk_mul_f32 v[40:41], v[40:41], v[44:45]
	s_nop 1
	v_mfma_f32_16x16x16_bf16 v[116:119], v[12:13], v[8:9], v[40:43]
	v_mov_b32_e32 v0, v14
	v_mov_b32_e32 v1, v15
	ds_read_b128 v[12:15], v108 offset:14336
	v_pk_mul_f32 v[38:39], v[38:39], v[50:51]
	v_pk_mul_f32 v[36:37], v[36:37], v[48:49]
	s_nop 1
	v_mfma_f32_16x16x16_bf16 v[8:11], v[0:1], v[8:9], v[36:39]
	s_nop 2
	ds_read_b128 v[36:39], v108 offset:14400
	ds_read_b128 v[40:43], v108 offset:12032
	ds_read_b128 v[44:47], v108 offset:12096
	s_waitcnt lgkmcnt(1)
	v_mfma_f32_16x16x32_bf16 v[12:15], v[12:15], v[40:43], 0
	s_waitcnt lgkmcnt(0)
	v_mfma_f32_16x16x32_bf16 v[12:15], v[36:39], v[44:47], v[12:15]
	v_add_u32_e32 v36, 0x2800, v115
	v_cvt_pk_bf16_f32 v44, v16, v17
	v_cvt_pk_bf16_f32 v45, v18, v19
	v_cvt_pk_bf16_f32 v46, v4, v5
	v_cvt_pk_bf16_f32 v47, v6, v7
	s_nop 2
	v_cndmask_b32_e64 v0, v12, 0, s[6:7]
	v_cndmask_b32_e64 v1, 0, v13, s[8:9]
	v_cvt_pk_bf16_f32 v0, v0, v1
	v_cndmask_b32_e64 v1, v14, 0, s[10:11]
	v_cndmask_b32_e64 v2, v15, 0, s[12:13]
	ds_read2_b64 v[12:15], v36 offset0:224 offset1:228
	ds_read2_b64 v[36:39], v36 offset0:232 offset1:236
	v_cvt_pk_bf16_f32 v1, v1, v2
	ds_read_b64 v[126:127], v109 offset:18688
	v_mov_b32_e32 v2, v3
	s_waitcnt lgkmcnt(2)
	v_bfi_b32 v14, s30, v14, v14
	s_waitcnt lgkmcnt(1)
	v_bfi_b32 v38, s30, v38, v38
	s_waitcnt lgkmcnt(0)
	v_mfma_f32_16x16x32_bf16 v[40:43], v[0:3], v[126:129], 0
	v_mfma_f32_16x16x32_bf16 v[12:15], v[12:15], v[44:47], v[40:43]
	s_nop 6
	v_cvt_pk_bf16_f32 v40, v116, v117
	v_cvt_pk_bf16_f32 v41, v118, v119
	v_cvt_pk_bf16_f32 v42, v8, v9
	v_cvt_pk_bf16_f32 v43, v10, v11
	s_nop 1
	v_mfma_f32_16x16x32_bf16 v[12:15], v[36:39], v[40:43], v[12:15]
	s_nop 7
	v_cvt_pk_bf16_f32 v0, v12, s0
	ds_write_b16 v110, v0 offset:52352
	v_cvt_pk_bf16_f32 v0, v13, s0
	ds_write_b16 v110, v0 offset:52616
	v_cvt_pk_bf16_f32 v0, v14, s0
	ds_write_b16 v110, v0 offset:52880
	v_cvt_pk_bf16_f32 v0, v15, s0
	ds_write_b16 v110, v0 offset:53144
	ds_read2st64_b64 v[12:15], v124 offset0:32 offset1:33
	ds_read2st64_b64 v[36:39], v124 offset0:34 offset1:35
	ds_read_b128 v[40:43], v112 offset:23808
	ds_read_b128 v[44:47], v112 offset:23872
	s_waitcnt lgkmcnt(3)
	s_waitcnt lgkmcnt(1)
	v_pk_mul_f32 v[18:19], v[18:19], v[42:43]
	v_pk_mul_f32 v[16:17], v[16:17], v[40:41]
	s_waitcnt lgkmcnt(0)
	v_pk_mul_f32 v[6:7], v[6:7], v[46:47]
	v_pk_mul_f32 v[4:5], v[4:5], v[44:45]
	v_mfma_f32_16x16x16_bf16 v[40:43], v[12:13], v[126:127], v[16:19]
	v_mov_b32_e32 v0, v14
	v_mov_b32_e32 v1, v15
	ds_read_b128 v[12:15], v112 offset:24000
	s_nop 0
	v_mfma_f32_16x16x16_bf16 v[44:47], v[0:1], v[126:127], v[4:7]
	s_nop 1
	ds_read_b128 v[4:7], v112 offset:23936
	s_waitcnt lgkmcnt(0)
	s_barrier
; __device__ __forceinline__ unsigned pk2(float lo, float hi) { f32x2_t v = {lo, hi}; bf16x2_t b = __builtin_convertvector(v, bf16x2_t); return __builtin_bit_cast(unsigned, b); }
; __device__ __forceinline__ float lo_bf(unsigned u) { return __uint_as_float(u << 16); }
; __device__ __forceinline__ float hi_bf(unsigned u) { return __uint_as_float(u & 0xffff0000u); }
; template <int MODE>
; __device__ void scan_unit(int swave, const Params& p, int j, int b, int h, int dir, char* shm) {
;     ...
;   auto load_raw = [&](int c, Raw& R) {
;     const int tok = tokof(c, ti);
;     const bf16_t* row = P + (rowbase + tok) * LDP;
;     if (MODE == 0) {
;       R.q = *(const unsigned*)(row + E_GQ + h * 64 + dp); R.k = *(const unsigned*)(row + E_GK + h * 64 + dp);
;       const uint4* lrp = (const uint4*)(row + (dir ? E_GLB : E_GLF));
;       R.lr0 = lrp[0]; R.lr1 = lrp[1];
;       R.v = *(const uint2*)(row + E_GV + h * 128 + vg * 4);
;     } else if (MODE == 1) {
;       R.q = *(const unsigned*)(row + E_HQ + h * 64 + dp); R.k = *(const unsigned*)(row + (dir ? E_HZB : E_HZF) + h * 64 + dp);
;       R.v = *(const uint2*)(row + E_HI + h * 128 + vg * 4);
;     } else {
;       R.q = *(const unsigned*)(row + O_RQ + h * 128 + dp); R.q2 = *(const unsigned*)(row + O_RQ + h * 128 + 64 + dp);
;       R.k = *(const unsigned*)(row + O_RK + h * 128 + dp); R.k2 = *(const unsigned*)(row + O_RK + h * 128 + 64 + dp);
;       R.cs = *(const float4*)(rope + tok * 64 + dp);
;       const unsigned* vp = (const unsigned*)(row + O_RV + h * 192 + vg * 6);
;       R.v30 = vp[0]; R.v31 = vp[1]; R.v32 = vp[2];
;     }
;   };
;     ...
;   auto ostore = [&](int c, const bf16_t* obuf) {
;     for (int idx = tid; idx < 16 * DV / 4; idx += 512) {
;       const int i = idx / (DV / 4), cc = (idx % (DV / 4)) * 4;
;       uint2 o = *(const uint2*)(obuf + i * OS + cc);
;       if (KS == 2) {
;         const uint2 o2 = *(const uint2*)(obuf + (16 + i) * OS + cc);
;         o.x = pk2(lo_bf(o.x) + lo_bf(o2.x), hi_bf(o.x) + hi_bf(o2.x)); o.y = pk2(lo_bf(o.y) + lo_bf(o2.y), hi_bf(o.y) + hi_bf(o2.y));
;       }
;       *(uint2*)(O + (rowbase + tokof(c, i)) * OLD + cc) = o;
;     }
	s_waitcnt lgkmcnt(0)
	v_pk_mul_f32 v[6:7], v[118:119], v[6:7]
	v_pk_mul_f32 v[4:5], v[116:117], v[4:5]
	s_waitcnt vmcnt(5)
	s_waitcnt vmcnt(0)
	v_mfma_f32_16x16x16_bf16 v[48:51], v[36:37], v[126:127], v[4:7]
	v_mov_b32_e32 v0, v38
	v_mov_b32_e32 v1, v39
	s_nop 0
	v_pk_mul_f32 v[6:7], v[10:11], v[14:15]
	v_pk_mul_f32 v[4:5], v[8:9], v[12:13]
	s_nop 1
	v_mfma_f32_16x16x16_bf16 v[36:39], v[0:1], v[126:127], v[4:7]
	s_add_i32 s16, s28, 0x60
	s_and_b64 s[2:3], s[2:3], exec
	s_cselect_b32 s2, s16, 0x7e0
	v_or_b32_e32 v2, s2, v99
	v_sub_u32_e32 v0, 0x7ff, v2
	v_cndmask_b32_e64 v0, v0, v2, s[0:1]
	v_ashrrev_i32_e32 v1, 31, v0
	v_lshl_add_u64 v[0:1], s[18:19], 0, v[0:1]
	v_mov_b64_e32 v[4:5], s[46:47]
	v_mad_u64_u32 v[6:7], s[2:3], v0, s53, v[4:5]
	v_mad_i32_i24 v7, v1, s53, v7
	v_lshl_add_u64 v[0:1], v[6:7], 0, s[94:95]
	v_lshl_add_u64 v[0:1], v[0:1], 0, v[82:83]
	s_mov_b32 s45, s95
	s_mov_b32 s51, s95
	v_lshl_add_u64 v[8:9], v[6:7], 0, s[44:45]
	global_load_dword v119, v[0:1], off
	global_load_dword v118, v[0:1], off offset:512
	global_load_dwordx4 v[16:19], v[8:9], off
	v_lshl_add_u64 v[0:1], v[6:7], 0, s[50:51]
	v_lshl_add_u64 v[0:1], v[0:1], 0, v[84:85]
	global_load_dwordx4 v[12:15], v[8:9], off offset:16
	global_load_dwordx2 v[94:95], v[0:1], off offset:1024
	v_or_b32_e32 v0, 16, v2
	v_sub_u32_e32 v1, 0x7ff, v0
	v_cndmask_b32_e64 v0, v1, v0, s[0:1]
	v_ashrrev_i32_e32 v1, 31, v0
	v_lshl_add_u64 v[0:1], s[18:19], 0, v[0:1]
	v_mad_u64_u32 v[4:5], s[2:3], v0, s53, v[4:5]
	v_mad_i32_i24 v5, v1, s53, v5
	v_lshl_add_u64 v[0:1], v[4:5], 0, s[94:95]
	v_lshl_add_u64 v[0:1], v[0:1], 0, v[82:83]
	v_lshl_add_u64 v[6:7], v[4:5], 0, s[44:45]
	global_load_dword v117, v[0:1], off
	global_load_dword v116, v[0:1], off offset:512
	global_load_dwordx4 v[8:11], v[6:7], off
	v_lshl_add_u64 v[0:1], v[4:5], 0, s[50:51]
	v_lshl_add_u64 v[0:1], v[0:1], 0, v[84:85]
	global_load_dwordx4 v[4:7], v[6:7], off offset:16
	s_nop 0
	global_load_dwordx2 v[90:91], v[0:1], off offset:1024
	s_and_saveexec_b64 s[2:3], s[4:5]
	s_cbranch_execz .LBB0_691
	s_sub_i32 vcc_lo, 0x7e0, s28
	s_cmp_lg_u64 s[0:1], 0
	s_cselect_b32 vcc_lo, s28, vcc_lo
	s_add_i32 vcc_lo, vcc_lo, s18
	s_lshl_b32 vcc_lo, vcc_lo, 11
	s_add_u32 s16, s48, vcc_lo
	s_addc_u32 s17, s49, 0
	v_add_u32_e32 v160, v113, v166
	v_add_u32_e32 v161, v114, v166
	ds_read_b64 v[162:163], v160
	ds_read_b64 v[164:165], v161
	s_waitcnt lgkmcnt(1)
	global_store_dwordx2 v167, v[162:163], s[16:17]
	s_waitcnt lgkmcnt(0)
	global_store_dwordx2 v168, v[164:165], s[16:17]
